# s5_fill rewritten by hand (wave owns whole rows of WE/WY, exp/sincos once per (group,state,distance) with the compiler's own instruction sequence, 16-byte stores), work split over all workgroups by bl
# speedup vs baseline: 1.0587x; 1.0127x over previous
; DI int opqv(int x) { asm volatile("" : "+v"(x)); return x; }
; DI char* opq(char* p) { asm volatile("" : "+s"(p)); return p; }
; DI void s5_fill(const Params& p, int j) {
;   const int tid = opqv(threadIdx.x), nb = gridDim.x, bid = blockIdx.x;
;   char* ws = opq(p.ws);
;   const float4* s5z = (const float4*)(ws + OFF_S5Z) + j * 2048; const float2* bbar = (const float2*)(ws + OFF_BBAR) + j * 2048 * 16;
;   const float* ktab = (const float*)(ws + OFF_KTAB) + (size_t)j * 32 * 32 * 256;
;   u16* WE = (u16*)(ws + OFF_WE); u16* WY = (u16*)(ws + OFF_WY);
;   for (int idx = bid * NTHR + tid; idx < 32 * 256 * 512; idx += nb * NTHR) {
;     const int g = idx >> 17, n2 = (idx >> 9) & 255, k = idx & 511, jj = k >> 4, q = k & 15, n = n2 & 63;
;     if (n2 >= 128) { WE[idx] = 0; continue; }
;     const float4 z = s5z[g * 64 + n];
.Lri_pp_trail:
.LBB0_819:
	s_waitcnt vmcnt(0) lgkmcnt(0)
	v_readlane_b32 s10, v251, 13
	v_readlane_b32 s11, v251, 14
	v_readlane_b32 s85, v254, 25
	v_readlane_b32 s22, v251, 0
	s_mov_b32 s23, s16
	v_lshrrev_b32_e32 v0, 6, v182
	v_and_b32_e32 v8, 63, v182
	v_readfirstlane_b32 s20, v0
	s_lshl_b32 s0, s22, 3
	s_add_u32 s20, s20, s0
	s_lshl_b32 s35, s23, 3
	s_lshl_b32 s0, s85, 15
	s_add_u32 s8, s10, s0
	s_addc_u32 s9, s11, 0
	s_add_u32 s8, s8, 0xe34100
	s_addc_u32 s9, s9, 0
	s_lshl_b32 s0, s85, 18
	s_add_u32 s12, s10, s0
	s_addc_u32 s13, s11, 0
	s_add_u32 s12, s12, 0xe44100
	s_addc_u32 s13, s13, 0
	s_add_u32 s14, s10, 0x7004100
	s_addc_u32 s15, s11, 0
	s_lshl_b32 s0, s85, 20
	s_add_u32 s22, s10, s0
	s_addc_u32 s23, s11, 0
	s_add_u32 s22, s22, 0xec4100
	s_addc_u32 s23, s23, 0
	s_add_u32 s10, s10, 0x7804100
	s_addc_u32 s11, s11, 0
	s_lshl_b32 s0, s85, 17
	v_readlane_b32 s24, v254, 4
	v_readlane_b32 s25, v254, 5
	s_add_u32 s24, s24, s0
	s_addc_u32 s25, s25, 0
	v_readlane_b32 s28, v254, 6
	v_readlane_b32 s29, v254, 7
	s_add_u32 s28, s28, s0
	s_addc_u32 s29, s29, 0
	s_lshl_b32 s0, s85, 11
	v_readlane_b32 s76, v254, 8
	v_readlane_b32 s77, v254, 9
	s_add_u32 s76, s76, s0
	s_addc_u32 s77, s77, 0
	v_and_b32_e32 v9, 31, v8
	v_lshrrev_b32_e32 v10, 5, v8
	v_lshlrev_b32_e32 v11, 4, v8
	v_mov_b32_e32 v28, 0
	v_mov_b32_e32 v29, 0
	v_mov_b32_e32 v30, 0
	v_mov_b32_e32 v31, 0
	s_mov_b32 s34, s20
